# LDS bank conflicts: K-tile XOR swizzle widened from 8 to 16 rows in both attention phases so ds_read_b128 of K is conflict-free (writer and reader address math changed consistently)
# speedup vs baseline: 1.0090x; 1.0090x over previous
; #define LAS __attribute__((address_space(3)))
; __device__ __forceinline__ int my_tid() { int t = threadIdx.x; asm volatile("" : "+v"(t)); return t; }
; __device__ __forceinline__ void phase_mix0(const Params& p, LP lds) {
;     ...
;   const int tid = my_tid(), sc = (tid & 15) * 8;
;   const bf16_t* KV = (const bf16_t*)(p.ws + WS_KV); const bf16_t* QM = (const bf16_t*)(p.ws + WS_QM); const bf16_t* KPE = (const bf16_t*)(p.ws + WS_KPE);
;   bf16_t* MIX = (bf16_t*)(p.ws + WS_H);
;   const float scale = 0.10206207261596577f;
;   const float Cs = scale * 1.4426950408889634f, thr = 8.f / scale;
;   int* ctr = (int*)(p.ws + WS_CTR) + (blockIdx.x & 7);
;   LAS int* slot = (LAS int*)(lds + 69632);
;   for (;;) {
;     __syncthreads();
;     if (tid == 0) *slot = atomicAdd(ctr, 1);
;     __syncthreads();
;     const int t = *slot;
;     if (t >= 132) break;
;     int b, h, row0, seq;
;     if (t < 128) { const int bh = (t >> 5) * 8 + (blockIdx.x & 7), qb = t & 31; b = bh >> 3; h = bh & 7; row0 = b * TPB + CTXL + qb * 256; seq = TPB; }
;     else { const int bh = (t - 128) * 8 + (blockIdx.x & 7); b = bh >> 3; h = bh & 7; row0 = b * TPB; seq = CTXL; }
;     const size_t kb = (size_t)b * TPB;
;     const bf16_t* kptr = sc < 64 ? KV + kb * 1024 + h * 128 + sc : KPE + kb * 32 + ((sc - 64) & 31);
;     const int kstr = sc < 64 ? 1024 : 32;
;     const bf16_t* vptr = KV + kb * 1024 + h * 128 + 64 + (sc & 63);
.LBB0_1471:
	v_readlane_b32 s0, v254, 0
	v_mov_b32_e32 v2, v190
	v_readlane_b32 s1, v254, 1
	s_load_dwordx2 s[4:5], s[0:1], 0xf8
	s_and_b32 s9, s33, 7
	s_lshl_b32 s0, s9, 2
	v_lshlrev_b32_e32 v4, 4, v2
	v_lshlrev_b32_e32 v0, 3, v2
	s_waitcnt lgkmcnt(0)
	s_add_u32 s0, s4, s0
	s_addc_u32 s1, s5, 0
	v_and_b32_e32 v136, 48, v4
	v_mov_b32_e32 v137, 0
	v_and_b32_e32 v3, 0x78, v0
	s_add_u32 s24, s0, 0x1efb8100
	v_lshl_add_u64 v[0:1], s[4:5], 0, v[136:137]
	s_mov_b64 s[6:7], 0x1a786000
	s_addc_u32 s25, s1, 0
	v_lshl_add_u64 v[138:139], v[0:1], 0, s[6:7]
	s_lshl_b32 s12, s9, 7
	s_lshl_b32 s6, s9, 8
	s_add_u32 s6, s4, s6
	s_addc_u32 s7, s5, 0
	s_add_u32 s10, s6, 0x11b46000
	s_addc_u32 s11, s7, 0
	s_mulk_i32 s9, 0xc0
	s_add_u32 s9, s4, s9
	s_addc_u32 s13, s5, 0
	s_add_u32 s27, s9, 0x15d46000
	s_addc_u32 s35, s13, 0
	v_lshlrev_b32_e32 v136, 1, v3
	s_add_u32 s4, s4, s12
	v_lshl_add_u64 v[140:141], s[10:11], 0, v[136:137]
	s_addc_u32 s5, s5, 0
	v_and_b32_e32 v136, 0x70, v4
	v_and_b32_e32 v0, 7, v2
	s_add_u32 s36, s4, 0x3a76000
	v_lshl_add_u64 v[142:143], s[10:11], 0, v[136:137]
	v_lshlrev_b32_e32 v136, 4, v0
	s_addc_u32 s37, s5, 0
	v_lshl_add_u64 v[0:1], s[6:7], 0, v[136:137]
	s_mov_b64 s[4:5], 0x11bd6080
	s_add_i32 s39, 0, 0x11000
	s_mov_b32 s8, 0
	v_cmp_eq_u32_e64 s[0:1], 0, v2
	v_cmp_lt_u32_e64 s[2:3], 63, v3
	s_movk_i32 s38, 0xf0
	v_lshl_add_u64 v[144:145], v[0:1], 0, s[4:5]
	v_mov_b32_e32 v162, s39
	s_movk_i32 s40, 0x83
	s_movk_i32 s41, 0x600
	s_add_i32 s74, 0, 0x10000
	s_movk_i32 s42, 0xffe0
	s_movk_i32 s43, 0x60
	s_movk_i32 s44, 0x80
	s_movk_i32 s45, 0xa0
	s_mov_b32 s46, 0x429cc470
	s_mov_b32 s26, 0x3e16c740
	s_movk_i32 s47, 0x4000
	s_add_i32 s75, 0, 0x4000
	s_mov_b32 s48, 0xfffd0000
	s_mov_b32 s49, 0xfffe0000
	s_mov_b64 s[28:29], 0x40000
	s_movk_i32 s50, 0x1000
	s_movk_i32 s51, 0x5000
	s_mov_b32 s52, 0x8000
	s_mov_b32 s53, 0x9000
	s_mov_b32 s54, 0xc000
	s_mov_b32 s55, 0xd000
	v_mov_b32_e32 v163, 0x84000
	v_mov_b32_e32 v164, 0x1080000
	v_mov_b32_e32 v165, 0xf149f2ca
	s_branch .LBB0_1474

; __device__ __forceinline__ int v_st(int k, int c) { const int kk = (k & ~0xC) | ((k & 4) << 1) | ((k & 8) >> 1); return ((kk >> 3) * 4 + (c >> 5)) * 512 + ((kk & 7) * 32 + (c & 31)) * 2; }
; __device__ __forceinline__ int v_rd_base(int lane) { return ((lane & 3) << 3) | (((lane >> 2) & 3) << 6) | (((lane >> 4) & 1) << 5) | (((lane >> 5) & 1) << 8); }
; #define SLOAD(i, k0) do { sr_[i].vs0 = *reinterpret_cast<const bf16x8*>(vptr + (size_t)((k0) + sr) * vstr); \
;     sr_[i].vs1 = *reinterpret_cast<const bf16x8*>(vptr + (size_t)((k0) + 32 + sr) * vstr); \
;     sr_[i].ks0 = *reinterpret_cast<const bf16x8*>(kptr + (size_t)((k0) + sr) * kstr); \
;     sr_[i].ks1 = *reinterpret_cast<const bf16x8*>(kptr + (size_t)((k0) + 32 + sr) * kstr); } while (0)
; #define SWRITE(b, i) do { *(LAS bf16x8*)(V_lds + (b) * SHM_V + vst0) = sr_[i].vs0;          \
;     *(LAS bf16x8*)(V_lds + (b) * SHM_V + vst1) = sr_[i].vs1; const int kc = sc * 2;               \
;     *(LAS bf16x8*)(K_lds + (b) * SHM_K + KSWZ(sr, kc)) = sr_[i].ks0;                       \
;     *(LAS bf16x8*)(K_lds + (b) * SHM_K + KSWZ(32 + sr, kc)) = sr_[i].ks1; } while (0)
; template <int NDQ, int NDV> ...
;     ...
;   const bf16_t* Qw = Qb + (size_t)(wid * 32 + r32) * ldq + hi * 8;
; #pragma unroll
;   for (int d0 = 0; d0 < NDQ; ++d0) qr[d0] = *reinterpret_cast<const bf16x8*>(Qw + d0 * 16);
;   const int sr = tid >> 4, sc = (tid & 15) * 8, vst0 = v_st(sr, sc), vst1 = v_st(32 + sr, sc);
;   const int vb0 = (int)(unsigned)(size_t)V_lds + v_rd_base(lane);
;   struct { bf16x8 vs0, vs1, ks0, ks1; } sr_[2];
;     ...
;   f32x16 pA0, pA1, pB0, pB1; float mnA, mnB, alA, alB; bf16x8 pa0, pa1, pa2, pa3; const int NT = seq / 64;
;   constexpr int SE = 0, SO = 1;
;   __syncthreads();
;   SLOAD(SE, 0); asm volatile("s_waitcnt vmcnt(0)" ::: "memory"); SWRITE(0, SE); __syncthreads();
;   qkt<NDQ>(pA0, pA1, K_lds, qr, r32, hi); partialSM(pA0, pA1, m_reg, mnA, alA, Cs, thr);
.LBB0_1483:
	s_mul_hi_i32 s5, s9, 0x1080000
	s_mul_i32 s4, s9, 0x1080000
	s_and_saveexec_b64 s[6:7], s[2:3]
	s_xor_b64 s[6:7], exec, s[6:7]
	v_mad_i64_i32 v[150:151], s[10:11], s9, v163, v[138:139]
	s_or_saveexec_b64 s[6:7], s[6:7]
	v_mov_b64_e32 v[48:49], 32
	v_mov_b64_e32 v[50:51], s[4:5]
	s_xor_b64 exec, exec, s[6:7]
	v_mad_i64_i32 v[150:151], s[10:11], s9, v164, v[140:141]
	v_mov_b64_e32 v[48:49], 0x400
	v_mov_b64_e32 v[50:51], s[4:5]
	s_or_b64 exec, exec, s[6:7]
	s_ashr_i32 s31, s30, 31
	s_mul_i32 s4, s30, 0x600
	s_mul_hi_i32 s5, s30, 0x600
	s_add_u32 s4, s27, s4
	v_mov_b32_e32 v49, v190
	s_addc_u32 s5, s35, s5
	v_mov_b64_e32 v[0:1], s[4:5]
	v_ashrrev_i32_e32 v58, 1, v49
	v_ashrrev_i32_e32 v52, 4, v49
	v_bfe_u32 v166, v49, 5, 1
	v_bfi_b32 v2, s42, v58, v49
	v_add_u32_e32 v16, 32, v52
	v_mad_i64_i32 v[0:1], s[4:5], v2, s41, v[0:1]
	v_lshlrev_b32_e32 v146, 4, v166
	v_mov_b32_e32 v147, v137
	v_ashrrev_i32_e32 v53, 31, v52
	v_ashrrev_i32_e32 v17, 31, v16
	v_lshl_add_u64 v[56:57], v[142:143], 0, v[50:51]
	v_lshl_add_u64 v[0:1], v[0:1], 0, v[146:147]
	v_lshlrev_b64 v[54:55], 11, v[52:53]
	v_lshlrev_b64 v[2:3], 11, v[16:17]
	v_mad_i64_i32 v[8:9], s[4:5], v48, v52, 0
	v_mad_i64_i32 v[10:11], s[4:5], v48, v16, 0
	global_load_dwordx4 v[84:87], v[0:1], off
	global_load_dwordx4 v[80:83], v[0:1], off offset:32
	global_load_dwordx4 v[76:79], v[0:1], off offset:64
	global_load_dwordx4 v[72:75], v[0:1], off offset:96
	global_load_dwordx4 v[68:71], v[0:1], off offset:128
	global_load_dwordx4 v[64:67], v[0:1], off offset:160
	v_lshl_add_u64 v[0:1], v[56:57], 0, v[54:55]
	v_lshl_add_u64 v[4:5], v[56:57], 0, v[2:3]
	v_lshl_add_u64 v[8:9], v[8:9], 1, v[150:151]
	v_lshl_add_u64 v[12:13], v[10:11], 1, v[150:151]
	s_waitcnt vmcnt(63) expcnt(7) lgkmcnt(15)
	s_barrier
	global_load_dwordx4 v[0:3], v[0:1], off offset:128
	s_nop 0
	global_load_dwordx4 v[4:7], v[4:5], off offset:128
	s_nop 0
	global_load_dwordx4 v[8:11], v[8:9], off
	s_nop 0
	global_load_dwordx4 v[12:15], v[12:13], off
	v_lshlrev_b32_e32 v17, 3, v49
	v_and_b32_e32 v20, 0xfffff0, v52
	v_lshlrev_b32_e32 v21, 1, v52
	v_lshrrev_b32_e32 v22, 1, v52
	v_and_b32_e32 v23, 3, v52
	v_and_b32_e32 v19, 0x78, v17
	v_and_or_b32 v20, v21, 8, v20
	v_and_or_b32 v21, v22, 4, v23
	v_and_b32_e32 v22, 0xfffff0, v16
	v_lshlrev_b32_e32 v23, 1, v16
	v_and_b32_e32 v18, 0xf0, v49
	v_bfe_u32 v17, v17, 5, 2
	v_lshlrev_b32_e32 v24, 8, v52
	v_lshlrev_b32_e32 v19, 1, v19
	v_lshlrev_b32_e32 v16, 8, v16
	v_lshrrev_b32_e32 v20, 1, v20
	v_and_or_b32 v22, v23, 8, v22
	s_waitcnt vmcnt(11)
	v_and_b32_e32 v26, 48, v19
	v_bitop3_b32 v23, v19, v24, v18 bitop3:0xde
	v_bitop3_b32 v16, v19, v16, v18 bitop3:0xde
	v_or_b32_e32 v18, v20, v17
	v_lshrrev_b32_e32 v19, 1, v22
	v_and_b32_e32 v147, 31, v49
	v_lshlrev_b32_e32 v53, 4, v49
	v_lshlrev_b32_e32 v21, 6, v21
	v_add_u32_e32 v172, 0, v16
	v_lshlrev_b32_e32 v16, 9, v18
	v_or_b32_e32 v17, v19, v17
	v_lshl_add_u32 v62, v147, 8, 0
	v_bitop3_b32 v25, v146, v53, s38 bitop3:0x78
	v_or3_b32 v16, v16, v21, v26
	v_lshlrev_b32_e32 v17, 9, v17
	v_or3_b32 v17, v17, v21, v26
	v_add_u32_e32 v173, 0, v16
	v_add_u32_e32 v175, v62, v25
	v_add_u32_e32 v171, 0, v23
	s_waitcnt vmcnt(0)
	v_add_u32_e32 v174, 0, v17
	v_and_b32_e32 v121, 63, v49
	v_and_b32_e32 v148, 0xffffffe0, v58
	v_add_u32_e32 v96, 0x80, v52
	v_ashrrev_i32_e32 v97, 31, v96
	s_mov_b32 s9, s8
	s_mov_b32 s10, s8
	s_mov_b32 s11, s8
	s_mov_b32 s12, s8
	s_mov_b32 s13, s8
	s_mov_b32 s14, s8
	s_mov_b32 s15, s8
	s_mov_b32 s16, s8
	s_waitcnt vmcnt(3)
	ds_write_b128 v173, v[0:3]
	s_waitcnt vmcnt(2)
	ds_write_b128 v174, v[4:7]
	s_waitcnt vmcnt(1)
	ds_write_b128 v171, v[8:11] offset:32768
	s_waitcnt vmcnt(0)
	ds_write_b128 v172, v[12:15] offset:32768
	s_waitcnt lgkmcnt(0)
	s_barrier
	ds_read_b128 v[0:3], v175 offset:32768
	ds_read_b128 v[4:7], v175 offset:40960
	s_waitcnt lgkmcnt(1)
	v_mfma_f32_32x32x16_bf16 v[32:47], v[0:3], v[84:87], 0
	v_and_b32_e32 v12, 0xf0, v53
	v_bitop3_b32 v0, v146, v12, 32 bitop3:0x36
	v_add_u32_e32 v176, v62, v0
	v_and_b32_e32 v8, 0x3fffffc0, v49
	v_lshl_add_u32 v149, v8, 2, s74
	v_add_u32_e32 v8, 0x60, v52
	v_ashrrev_i32_e32 v9, 31, v8
	s_waitcnt lgkmcnt(0)
	v_mfma_f32_32x32x16_bf16 v[16:31], v[4:7], v[84:87], 0
	ds_read_b128 v[0:3], v176 offset:32768
	ds_read_b128 v[4:7], v176 offset:40960
	v_lshlrev_b64 v[10:11], 11, v[8:9]
	v_lshl_add_u64 v[10:11], v[56:57], 0, v[10:11]
	v_lshlrev_b32_e32 v13, 3, v121
	v_and_b32_e32 v14, 0xc0, v53
	s_mov_b32 s17, s8
	s_mov_b32 s18, s8
	s_waitcnt lgkmcnt(1)
	v_mfma_f32_32x32x16_bf16 v[32:47], v[0:3], v[80:83], v[32:47]
	v_bitop3_b32 v0, v146, v12, 64 bitop3:0x36
	v_add_u32_e32 v177, v62, v0
	s_mov_b32 s19, s8
	s_mov_b32 s20, s8
	s_mov_b32 s21, s8
	s_mov_b32 s22, s8
	s_mov_b32 s23, s8
	s_waitcnt lgkmcnt(0)
	v_mfma_f32_32x32x16_bf16 v[16:31], v[4:7], v[80:83], v[16:31]
	ds_read_b128 v[0:3], v177 offset:32768
	ds_read_b128 v[4:7], v177 offset:40960
	s_mov_b32 s57, 4
	v_lshl_add_u32 v167, v147, 2, v149
	v_lshlrev_b32_e32 v136, 8, v48
	v_mov_b32_e32 v169, 0
	s_waitcnt lgkmcnt(1)
	v_mfma_f32_32x32x16_bf16 v[32:47], v[0:3], v[76:79], v[32:47]
	v_bitop3_b32 v0, v146, v12, s43 bitop3:0x36
	v_add_u32_e32 v178, v62, v0
	ds_read_b128 v[0:3], v178 offset:32768
	s_waitcnt lgkmcnt(1)
	v_mfma_f32_32x32x16_bf16 v[16:31], v[4:7], v[76:79], v[16:31]
	ds_read_b128 v[4:7], v178 offset:40960
	s_waitcnt lgkmcnt(1)
	v_mfma_f32_32x32x16_bf16 v[32:47], v[0:3], v[72:75], v[32:47]
	v_bitop3_b32 v0, v146, v12, s44 bitop3:0x36
	v_add_u32_e32 v179, v62, v0
	ds_read_b128 v[0:3], v179 offset:32768
	s_waitcnt lgkmcnt(1)
; #define SLOAD(i, k0) do { sr_[i].vs0 = *reinterpret_cast<const bf16x8*>(vptr + (size_t)((k0) + sr) * vstr); \
;     sr_[i].vs1 = *reinterpret_cast<const bf16x8*>(vptr + (size_t)((k0) + 32 + sr) * vstr); \
;     sr_[i].ks0 = *reinterpret_cast<const bf16x8*>(kptr + (size_t)((k0) + sr) * kstr); \
;     sr_[i].ks1 = *reinterpret_cast<const bf16x8*>(kptr + (size_t)((k0) + 32 + sr) * kstr); } while (0)
; #define SWRITE(b, i) do { *(LAS bf16x8*)(V_lds + (b) * SHM_V + vst0) = sr_[i].vs0;          \
;     *(LAS bf16x8*)(V_lds + (b) * SHM_V + vst1) = sr_[i].vs1; const int kc = sc * 2;               \
;     *(LAS bf16x8*)(K_lds + (b) * SHM_K + KSWZ(sr, kc)) = sr_[i].ks0;                       \
;     *(LAS bf16x8*)(K_lds + (b) * SHM_K + KSWZ(32 + sr, kc)) = sr_[i].ks1; } while (0)
; #define SWAIT() asm volatile("s_waitcnt vmcnt(4)" ::: "memory")
; __device__ __forceinline__ void partialSM(f32x16& p0, f32x16& p1, float& m_reg, float& mn, float& alpha, float C, float thr) {
;   float pmax = p0[0];
; #pragma unroll
;   for (int r = 1; r < 16; ++r) pmax = fmaxf(pmax, p0[r]);
; #pragma unroll
;   for (int r = 0; r < 16; ++r) pmax = fmaxf(pmax, p1[r]);
;   { auto rr = __builtin_amdgcn_permlane32_swap(__float_as_uint(pmax), __float_as_uint(pmax), false, false);
;     pmax = fmaxf(__uint_as_float(rr[0]), __uint_as_float(rr[1])); }
;   if (__builtin_expect(__all(pmax - m_reg <= thr), 1)) { mn = m_reg; alpha = 1.f; }
;   else { mn = fmaxf(m_reg, pmax); alpha = __builtin_amdgcn_exp2f((m_reg - mn) * C); m_reg = mn; }
;   const float mnC = -mn * C;
; #pragma unroll
;   for (int r = 0; r < 16; ++r) p0[r] = fmaf(p0[r], C, mnC);
; #pragma unroll
;   for (int r = 0; r < 16; ++r) p1[r] = fmaf(p1[r], C, mnC);
; #pragma unroll
;   for (int r = 0; r < 16; ++r) p0[r] = __builtin_amdgcn_exp2f(p0[r]);
; }
; template <int NDQ, int NDV> ...
;     ...
;   SLOAD(SO, 64); if (2 < NT) SLOAD(SE, 128);
;   SWAIT(); SWRITE(1, SO); __syncthreads();
	v_mfma_f32_32x32x16_bf16 v[16:31], v[4:7], v[72:75], v[16:31]
	v_add_u32_e32 v4, 64, v52
	v_ashrrev_i32_e32 v5, 31, v4
	v_lshlrev_b64 v[6:7], 11, v[4:5]
	v_lshl_add_u64 v[6:7], v[56:57], 0, v[6:7]
	v_mad_i64_i32 v[4:5], s[4:5], v48, v4, 0
	global_load_dwordx4 v[58:61], v[6:7], off offset:128
	global_load_dwordx4 v[104:107], v[10:11], off offset:128
	v_lshl_add_u64 v[4:5], v[4:5], 1, v[150:151]
	v_mad_i64_i32 v[6:7], s[4:5], v48, v8, 0
	v_lshl_add_u64 v[6:7], v[6:7], 1, v[150:151]
	global_load_dwordx4 v[108:111], v[4:5], off
	global_load_dwordx4 v[112:115], v[6:7], off
	v_lshlrev_b32_e32 v5, 1, v49
	s_waitcnt lgkmcnt(0)
	v_mfma_f32_32x32x16_bf16 v[32:47], v[0:3], v[68:71], v[32:47]
	v_bitop3_b32 v0, v146, v12, s45 bitop3:0x36
	v_and_or_b32 v4, v13, 24, v14
	v_and_b32_e32 v5, 32, v5
	v_and_b32_e32 v6, 0x100, v13
	v_add_u32_e32 v180, v62, v0
	v_or3_b32 v49, v4, v5, v6
	ds_read_b128 v[4:7], v179 offset:40960
	ds_read_b128 v[0:3], v180 offset:32768
	ds_read_b128 v[88:91], v180 offset:40960
	s_waitcnt lgkmcnt(1)
	v_mfma_f32_32x32x16_bf16 v[32:47], v[0:3], v[64:67], v[32:47]
	v_add_u32_e32 v170, 0, v49
	v_add_u32_e32 v168, s75, v49
	s_nop 9
	v_max_f32_e32 v53, v33, v33
	v_mfma_f32_32x32x16_bf16 v[16:31], v[4:7], v[68:71], v[16:31]
	v_max_f32_e32 v62, v32, v32
	v_max_f32_e32 v53, v62, v53
	v_max3_f32 v53, v53, v34, v35
	v_max3_f32 v53, v53, v36, v37
	v_max3_f32 v53, v53, v38, v39
	v_max3_f32 v53, v53, v40, v41
	v_max3_f32 v53, v53, v42, v43
	s_waitcnt lgkmcnt(0)
	v_mfma_f32_32x32x16_bf16 v[16:31], v[88:91], v[64:67], v[16:31]
	v_max3_f32 v53, v53, v44, v45
	v_max3_f32 v53, v53, v46, v47
	v_mad_i64_i32 v[90:91], s[4:5], v48, v96, 0
	v_lshl_add_u64 v[90:91], v[90:91], 1, v[150:151]
	v_lshlrev_b64 v[96:97], 11, v[96:97]
	v_mov_b64_e32 v[0:1], s[8:9]
	s_nop 5
	v_max3_f32 v53, v53, v16, v17
	v_max3_f32 v53, v53, v18, v19
	v_max3_f32 v53, v53, v20, v21
	v_max3_f32 v53, v53, v22, v23
	v_max3_f32 v53, v53, v24, v25
	v_max3_f32 v53, v53, v26, v27
	v_max3_f32 v53, v53, v28, v29
	v_max3_f32 v53, v53, v30, v31
	v_mov_b32_e32 v62, v53
	s_nop 1
	v_permlane32_swap_b32_e32 v53, v62
	v_max_f32_e32 v62, v62, v62
	v_max_f32_e32 v53, v53, v53
	v_max_f32_e32 v53, v53, v62
	v_add_u32_e32 v62, 0xa0, v52
	v_ashrrev_i32_e32 v63, 31, v62
	v_mad_i64_i32 v[88:89], s[4:5], v48, v62, 0
	v_lshlrev_b64 v[62:63], 11, v[62:63]
	v_lshl_add_u64 v[88:89], v[88:89], 1, v[150:151]
	v_lshl_add_u64 v[62:63], v[56:57], 0, v[62:63]
	global_load_dwordx4 v[92:95], v[88:89], off
	s_nop 0
	global_load_dwordx4 v[88:91], v[90:91], off
	v_lshl_add_u64 v[56:57], v[56:57], 0, v[96:97]
	global_load_dwordx4 v[100:103], v[62:63], off offset:128
	global_load_dwordx4 v[96:99], v[56:57], off offset:128
	v_add_f32_e32 v116, 0x7149f2ca, v53
	v_cmp_ge_f32_e32 vcc, s46, v116
	s_cmp_eq_u64 vcc, exec
	v_max_f32_e32 v53, 0xf149f2ca, v53
	s_cselect_b64 vcc, -1, 0
	v_cndmask_b32_e32 v120, v53, v165, vcc
	v_mul_f32_e32 v56, 0xbe16c740, v120
	v_fmamk_f32 v32, v32, 0x3e16c740, v56
	v_exp_f32_e32 v130, v32
	v_fmamk_f32 v32, v33, 0x3e16c740, v56
	v_exp_f32_e32 v134, v32
	v_fmamk_f32 v32, v34, 0x3e16c740, v56
	v_exp_f32_e32 v131, v32
	v_fmamk_f32 v32, v35, 0x3e16c740, v56
	v_exp_f32_e32 v135, v32
	v_fmamk_f32 v32, v36, 0x3e16c740, v56
	v_exp_f32_e32 v132, v32
	v_fmamk_f32 v32, v37, 0x3e16c740, v56
	v_exp_f32_e32 v185, v32
	v_fmamk_f32 v32, v38, 0x3e16c740, v56
	v_exp_f32_e32 v133, v32
	v_fmamk_f32 v32, v39, 0x3e16c740, v56
	v_exp_f32_e32 v186, v32
	v_fmamk_f32 v32, v40, 0x3e16c740, v56
	v_exp_f32_e32 v122, v32
	v_fmamk_f32 v32, v41, 0x3e16c740, v56
	v_exp_f32_e32 v125, v32
	v_fmamk_f32 v32, v42, 0x3e16c740, v56
	v_exp_f32_e32 v123, v32
	v_fmamk_f32 v32, v43, 0x3e16c740, v56
	v_exp_f32_e32 v126, v32
	v_fmamk_f32 v32, v44, 0x3e16c740, v56
	s_waitcnt vmcnt(4)
	s_waitcnt vmcnt(7)
	ds_write_b128 v173, v[58:61] offset:16384
	s_waitcnt vmcnt(6)
	ds_write_b128 v174, v[104:107] offset:16384
	s_waitcnt vmcnt(5)
	ds_write_b128 v171, v[108:111] offset:49152
	s_waitcnt vmcnt(4)
	ds_write_b128 v172, v[112:115] offset:49152
	v_exp_f32_e32 v124, v32
	v_fmamk_f32 v32, v45, 0x3e16c740, v56
	v_sub_f32_e32 v33, 0xf149f2ca, v53
	v_pk_fma_f32 v[114:115], v[18:19], s[26:27], v[56:57] op_sel_hi:[1,0,0]
	v_pk_fma_f32 v[116:117], v[16:17], s[26:27], v[56:57] op_sel_hi:[1,0,0]
	v_lshlrev_b32_e32 v18, 1, v48
	v_add_u32_e32 v16, 0x120, v52
	v_exp_f32_e32 v127, v32
	v_fmamk_f32 v32, v46, 0x3e16c740, v56
	v_mul_f32_e32 v33, 0x3e16c740, v33
	v_mad_i64_i32 v[152:153], s[6:7], v18, v16, 0
	v_lshl_add_u64 v[16:17], v[50:51], 0, v[54:55]
	v_exp_f32_e32 v33, v33
	v_exp_f32_e32 v128, v32
	v_fmamk_f32 v32, v47, 0x3e16c740, v56
	v_lshl_add_u64 v[154:155], v[144:145], 0, v[16:17]
	v_add_u32_e32 v16, 0x100, v52
	v_exp_f32_e32 v129, v32
	v_mad_i64_i32 v[156:157], s[6:7], v18, v16, 0
	v_add_u32_e32 v16, 0xe0, v52
	v_mov_b64_e32 v[14:15], s[22:23]
	v_mad_i64_i32 v[158:159], s[6:7], v18, v16, 0
	v_add_u32_e32 v16, 0xc0, v52
	v_mov_b64_e32 v[2:3], s[10:11]
	v_mov_b64_e32 v[4:5], s[12:13]
	v_mov_b64_e32 v[6:7], s[14:15]
	v_mov_b64_e32 v[8:9], s[16:17]
	v_mov_b64_e32 v[10:11], s[18:19]
	v_mov_b64_e32 v[12:13], s[20:21]
	v_pk_fma_f32 v[108:109], v[30:31], s[26:27], v[56:57] op_sel_hi:[1,0,0]
	v_pk_fma_f32 v[112:113], v[28:29], s[26:27], v[56:57] op_sel_hi:[1,0,0]
	v_pk_fma_f32 v[118:119], v[26:27], s[26:27], v[56:57] op_sel_hi:[1,0,0]
	v_pk_fma_f32 v[104:105], v[24:25], s[26:27], v[56:57] op_sel_hi:[1,0,0]
	v_pk_fma_f32 v[106:107], v[22:23], s[26:27], v[56:57] op_sel_hi:[1,0,0]
	v_pk_fma_f32 v[110:111], v[20:21], s[26:27], v[56:57] op_sel_hi:[1,0,0]
	v_mad_i64_i32 v[160:161], s[6:7], v18, v16, 0
	v_mov_b64_e32 v[30:31], v[14:15]
	v_cndmask_b32_e64 v181, v33, 1.0, vcc
	v_cmp_gt_u32_e64 s[4:5], 32, v121
	v_mov_b64_e32 v[28:29], v[12:13]
	v_mov_b64_e32 v[26:27], v[10:11]
	v_mov_b64_e32 v[24:25], v[8:9]
	v_mov_b64_e32 v[22:23], v[6:7]
	v_mov_b64_e32 v[20:21], v[4:5]
	v_mov_b64_e32 v[18:19], v[2:3]
	v_mov_b64_e32 v[16:17], v[0:1]
	s_waitcnt lgkmcnt(0)
	s_barrier

; __device__ __forceinline__ int my_tid() { int t = threadIdx.x; asm volatile("" : "+v"(t)); return t; }
; __device__ __forceinline__ void phase_mix1(const Params& p, LP lds) {
;   const int tid = my_tid(), sc = (tid & 15) * 8;
;   const bf16_t* Q = (const bf16_t*)(p.ws + WS_QKV1); bf16_t* MIX = (bf16_t*)(p.ws + WS_H);
;   const float scale = 0.08838834764831845f;
;   const float Cs = scale * 1.4426950408889634f, thr = 8.f / scale;
;   for (int t = blockIdx.x; t < 1024; t += gridDim.x) {
;     const int blkv = t & 255, rnd = t >> 8, bh = rnd * 8 + (blkv & 7), qb = blkv >> 3, b = bh >> 3, h = bh & 7, kvh = h >> 2;
;     const int row0 = b * TPB + CTXL + qb * 256;
;     const size_t kb = (size_t)b * TPB;
;     attn_body<8, 4>(Q + (size_t)row0 * 1536 + h * 128, 1536, Q + kb * 1536 + 1024 + kvh * 128 + sc, 1536, Q + kb * 1536 + 1280 + kvh * 128 + sc, 1536,
.LBB0_2119:
	s_or_b64 exec, exec, s[0:1]
	v_readlane_b32 s0, v254, 11
	v_readlane_b32 s1, v254, 12
	s_waitcnt lgkmcnt(0)
	v_mov_b32_e32 v0, v190
	s_and_b64 vcc, exec, s[0:1]
	s_barrier
	s_cbranch_vccnz .LBB0_2141
	v_readlane_b32 s0, v254, 0
	v_readlane_b32 s1, v254, 1
	s_load_dwordx2 s[0:1], s[0:1], 0xf8
	v_and_b32_e32 v2, 15, v0
	v_lshlrev_b32_e32 v1, 3, v0
	v_mov_b32_e32 v177, 0
	v_lshlrev_b32_e32 v176, 4, v2
	s_waitcnt lgkmcnt(0)
	s_add_u32 s5, s0, 0x7c76000
	s_addc_u32 s35, s1, 0
	s_add_u32 s38, s0, 0x3a76000
	v_and_b32_e32 v0, 0x78, v1
	s_addc_u32 s39, s1, 0
	v_lshl_add_u64 v[2:3], s[0:1], 0, v[176:177]
	s_mov_b64 s[0:1], 0x7d4ea00
	s_mov_b32 s12, 0
	v_lshl_add_u64 v[178:179], v[2:3], 0, s[0:1]
	s_movk_i32 s40, 0xc00
	v_lshlrev_b32_e32 v180, 1, v0
	v_mov_b32_e32 v181, v177
	s_movk_i32 s41, 0xffe0
	s_movk_i32 s42, 0xc0
	s_movk_i32 s43, 0xf0
	s_movk_i32 s44, 0x60
	s_movk_i32 s45, 0x80
	s_movk_i32 s46, 0xa0
	s_movk_i32 s47, 0xe0
	s_mov_b32 s48, 0x42b504f3
	s_mov_b32 s4, 0x3e0293ee
	v_mov_b32_e32 v186, 0xf149f2ca
	s_movk_i32 s49, 0x4000
	v_mov_b32_e32 v187, 0x18c0000
	s_mov_b32 s13, s12
	s_mov_b32 s14, s12
	s_mov_b32 s15, s12
	s_mov_b32 s16, s12
	s_mov_b32 s17, s12
	s_mov_b32 s18, s12
	s_mov_b32 s19, s12
	s_mov_b32 s20, s12
	s_mov_b32 s21, s12
	s_mov_b32 s22, s12
	s_mov_b32 s23, s12
	s_mov_b32 s24, s12
	s_mov_b32 s25, s12
	s_mov_b32 s26, s12
	s_mov_b32 s27, s12
	s_mov_b32 s50, 0xfffb8000
	s_mov_b32 s51, 0xfffd0000
	s_mov_b64 s[6:7], 0x60000
	s_movk_i32 s52, 0x1000
	s_movk_i32 s53, 0x5000
	s_mov_b32 s54, 0x8000
	s_mov_b32 s55, 0x9000
	s_mov_b32 s56, 0xc000
	s_mov_b32 s57, 0xd000
	s_mov_b32 s58, s33
	s_mov_b32 s59, s33
	s_branch .LBB0_2122

; #define SBAR() __builtin_amdgcn_sched_barrier(0)
; __device__ __forceinline__ int v_st(int k, int c) { const int kk = (k & ~0xC) | ((k & 4) << 1) | ((k & 8) >> 1); return ((kk >> 3) * 4 + (c >> 5)) * 512 + ((kk & 7) * 32 + (c & 31)) * 2; }
; __device__ __forceinline__ int v_rd_base(int lane) { return ((lane & 3) << 3) | (((lane >> 2) & 3) << 6) | (((lane >> 4) & 1) << 5) | (((lane >> 5) & 1) << 8); }
; #define SLOAD(i, k0) do { sr_[i].vs0 = *reinterpret_cast<const bf16x8*>(vptr + (size_t)((k0) + sr) * vstr); \
;     sr_[i].vs1 = *reinterpret_cast<const bf16x8*>(vptr + (size_t)((k0) + 32 + sr) * vstr); \
;     sr_[i].ks0 = *reinterpret_cast<const bf16x8*>(kptr + (size_t)((k0) + sr) * kstr); \
;     sr_[i].ks1 = *reinterpret_cast<const bf16x8*>(kptr + (size_t)((k0) + 32 + sr) * kstr); } while (0)
; #define SWAIT() asm volatile("s_waitcnt vmcnt(4)" ::: "memory")
; template <int NDQ, int NDV> ...
;     ...
;   const bf16_t* Qw = Qb + (size_t)(wid * 32 + r32) * ldq + hi * 8;
; #pragma unroll
;   for (int d0 = 0; d0 < NDQ; ++d0) qr[d0] = *reinterpret_cast<const bf16x8*>(Qw + d0 * 16);
;   const int sr = tid >> 4, sc = (tid & 15) * 8, vst0 = v_st(sr, sc), vst1 = v_st(32 + sr, sc);
;   const int vb0 = (int)(unsigned)(size_t)V_lds + v_rd_base(lane);
;   struct { bf16x8 vs0, vs1, ks0, ks1; } sr_[2];
;     ...
;   f32x16 pA0, pA1, pB0, pB1; float mnA, mnB, alA, alB; bf16x8 pa0, pa1, pa2, pa3; const int NT = seq / 64;
;   constexpr int SE = 0, SO = 1;
;   __syncthreads();
;   SLOAD(SE, 0); asm volatile("s_waitcnt vmcnt(0)" ::: "memory"); SWRITE(0, SE); __syncthreads();
;   qkt<NDQ>(pA0, pA1, K_lds, qr, r32, hi); partialSM(pA0, pA1, m_reg, mnA, alA, Cs, thr);
;   SLOAD(SO, 64); if (2 < NT) SLOAD(SE, 128);
;   SWAIT(); SWRITE(1, SO); __syncthreads();
;   for (int j = 1; j + 1 < NT; j += 2) {
;     SBAR(); qkt<NDQ>(pB0, pB1, K_lds + SHM_K, qr, r32, hi);
; __device__ __forceinline__ void phase_mix1(const Params& p, LP lds) {
;     ...
;   for (int t = blockIdx.x; t < 1024; t += gridDim.x) {
;     const int blkv = t & 255, rnd = t >> 8, bh = rnd * 8 + (blkv & 7), qb = blkv >> 3, b = bh >> 3, h = bh & 7, kvh = h >> 2;
;     const int row0 = b * TPB + CTXL + qb * 256;
;     const size_t kb = (size_t)b * TPB;
;     attn_body<8, 4>(Q + (size_t)row0 * 1536 + h * 128, 1536, Q + kb * 1536 + 1024 + kvh * 128 + sc, 1536, Q + kb * 1536 + 1280 + kvh * 128 + sc, 1536,
.LBB0_2122:
	s_ashr_i32 s3, s59, 8
	s_lshl_b32 s28, s59, 5
	s_mul_i32 s1, s3, 0x2100
	s_and_b32 s28, s28, 0x1f00
	s_add_i32 s1, s1, s28
	s_add_i32 s28, s1, 0x100
	s_and_b32 s2, s58, 4
	s_and_b32 s0, s59, 7
	s_ashr_i32 s29, s28, 31
	s_mul_i32 s30, s28, 0xc00
	s_mul_hi_i32 s1, s28, 0xc00
	s_add_u32 s30, s5, s30
	s_addc_u32 s1, s35, s1
	s_lshl_b32 s60, s0, 7
	s_lshl_b32 s0, s0, 8
	s_add_u32 s0, s30, s0
	s_addc_u32 s1, s1, 0
	s_mul_i32 s31, s3, 0x18c0000
	s_mul_hi_i32 s30, s3, 0x18c0000
	s_add_u32 s31, s5, s31
	s_addc_u32 s36, s35, s30
	s_lshl_b32 s30, s59, 6
	s_and_b32 s30, s30, 0x100
	v_mov_b32_e32 v58, v190
	s_add_u32 s30, s31, s30
	s_addc_u32 s31, s36, 0
	v_ashrrev_i32_e32 v59, 1, v58
	v_bfe_u32 v188, v58, 5, 1
	v_bfi_b32 v2, s41, v59, v58
	v_mov_b64_e32 v[0:1], s[0:1]
	v_ashrrev_i32_e32 v70, 4, v58
	v_lshl_add_u64 v[48:49], s[30:31], 0, v[180:181]
	v_mad_i64_i32 v[0:1], s[0:1], v2, s40, v[0:1]
	v_lshlrev_b32_e32 v176, 4, v188
	v_add_u32_e32 v16, 32, v70
	v_lshl_add_u64 v[0:1], v[0:1], 0, v[176:177]
	v_mad_i64_i32 v[8:9], s[0:1], v70, s40, v[48:49]
	v_mad_i64_i32 v[12:13], s[0:1], v16, s40, v[48:49]
	global_load_dwordx4 v[124:127], v[0:1], off
	global_load_dwordx4 v[120:123], v[0:1], off offset:32
	global_load_dwordx4 v[116:119], v[0:1], off offset:64
	global_load_dwordx4 v[112:115], v[0:1], off offset:96
	global_load_dwordx4 v[108:111], v[0:1], off offset:128
	global_load_dwordx4 v[104:107], v[0:1], off offset:160
	global_load_dwordx4 v[100:103], v[0:1], off offset:192
	global_load_dwordx4 v[96:99], v[0:1], off offset:224
	s_barrier
	global_load_dwordx4 v[0:3], v[8:9], off offset:2560
	global_load_dwordx4 v[4:7], v[12:13], off offset:2560
	s_nop 0
	global_load_dwordx4 v[8:11], v[8:9], off offset:2048
	s_nop 0
	global_load_dwordx4 v[12:15], v[12:13], off offset:2048
	v_lshlrev_b32_e32 v17, 3, v58
	v_and_b32_e32 v20, 0xfffff0, v70
	v_lshlrev_b32_e32 v21, 1, v70
	v_lshrrev_b32_e32 v22, 1, v70
	v_and_b32_e32 v23, 3, v70
	v_and_b32_e32 v19, 0x78, v17
	v_and_or_b32 v20, v21, 8, v20
	v_and_or_b32 v21, v22, 4, v23
	v_and_b32_e32 v22, 0xfffff0, v16
	v_lshlrev_b32_e32 v23, 1, v16
	v_and_b32_e32 v18, 0xf0, v58
	v_bfe_u32 v17, v17, 5, 2
	v_lshlrev_b32_e32 v24, 8, v70
	v_lshlrev_b32_e32 v19, 1, v19
	v_lshlrev_b32_e32 v16, 8, v16
	v_lshrrev_b32_e32 v20, 1, v20
	v_and_or_b32 v22, v23, 8, v22
	v_and_b32_e32 v25, 48, v19
	v_bitop3_b32 v23, v19, v24, v18 bitop3:0xde
	v_bitop3_b32 v16, v19, v16, v18 bitop3:0xde
	v_or_b32_e32 v18, v20, v17
	v_lshrrev_b32_e32 v19, 1, v22
	v_lshlrev_b32_e32 v21, 6, v21
	v_add_u32_e32 v196, 0, v16
	v_lshlrev_b32_e32 v16, 9, v18
	v_or_b32_e32 v17, v19, v17
	v_or3_b32 v16, v16, v21, v25
	v_lshlrev_b32_e32 v17, 9, v17
	v_and_b32_e32 v189, 31, v58
	v_lshlrev_b32_e32 v60, 4, v58
	v_or3_b32 v17, v17, v21, v25
	v_add_u32_e32 v197, 0, v16
	v_add_u32_e32 v195, 0, v23
	v_add_u32_e32 v198, 0, v17
	s_waitcnt vmcnt(0)
	v_lshl_add_u32 v61, v189, 8, 0
	v_and_b32_e32 v62, 0xf0, v60
	v_and_b32_e32 v71, 63, v58
	v_and_b32_e32 v63, 0x3fffffc0, v58
	v_lshlrev_b32_e32 v58, 1, v58
	v_and_b32_e32 v182, 0xffffffe0, v59
	v_lshlrev_b32_e32 v59, 3, v71
	v_and_b32_e32 v58, 32, v58
	v_lshl_add_u32 v183, v63, 2, s74
	v_mad_i64_i32 v[66:67], s[0:1], v70, s40, 0
	v_lshl_add_u32 v191, v189, 2, v183
	s_mov_b32 s61, -1
	s_waitcnt vmcnt(3)
	ds_write_b128 v197, v[0:3]
	s_waitcnt vmcnt(2)
	ds_write_b128 v198, v[4:7]
	s_waitcnt vmcnt(1)
	ds_write_b128 v195, v[8:11] offset:32768
	s_waitcnt vmcnt(0)
	ds_write_b128 v196, v[12:15] offset:32768
	v_bitop3_b32 v0, v176, v60, s43 bitop3:0x78
	v_add_u32_e32 v199, v61, v0
	s_waitcnt lgkmcnt(0)
	s_barrier
	ds_read_b128 v[0:3], v199 offset:32768
	ds_read_b128 v[4:7], v199 offset:40960
	s_waitcnt lgkmcnt(1)
	v_mfma_f32_32x32x16_bf16 v[32:47], v[0:3], v[124:127], 0
	v_bitop3_b32 v0, v176, v62, 32 bitop3:0x36
	v_add_u32_e32 v200, v61, v0
	v_and_b32_e32 v60, 0xc0, v60
	v_mov_b32_e32 v192, 0
	s_waitcnt lgkmcnt(0)
	v_mfma_f32_32x32x16_bf16 v[16:31], v[4:7], v[124:127], 0
	ds_read_b128 v[0:3], v200 offset:32768
	ds_read_b128 v[4:7], v200 offset:40960
	s_waitcnt lgkmcnt(1)
	v_mfma_f32_32x32x16_bf16 v[32:47], v[0:3], v[120:123], v[32:47]
	v_bitop3_b32 v0, v176, v62, 64 bitop3:0x36
	v_add_u32_e32 v201, v61, v0
	s_waitcnt lgkmcnt(0)
	v_mfma_f32_32x32x16_bf16 v[16:31], v[4:7], v[120:123], v[16:31]
	ds_read_b128 v[0:3], v201 offset:32768
	ds_read_b128 v[4:7], v201 offset:40960
	s_waitcnt lgkmcnt(1)
	v_mfma_f32_32x32x16_bf16 v[32:47], v[0:3], v[116:119], v[32:47]
	v_bitop3_b32 v0, v176, v62, s44 bitop3:0x36
	v_add_u32_e32 v202, v61, v0
	s_waitcnt lgkmcnt(0)
	v_mfma_f32_32x32x16_bf16 v[16:31], v[4:7], v[116:119], v[16:31]
	ds_read_b128 v[0:3], v202 offset:32768
	ds_read_b128 v[4:7], v202 offset:40960
	s_waitcnt lgkmcnt(1)
	v_mfma_f32_32x32x16_bf16 v[32:47], v[0:3], v[112:115], v[32:47]
	v_bitop3_b32 v0, v176, v62, s45 bitop3:0x36
	v_add_u32_e32 v203, v61, v0
	s_waitcnt lgkmcnt(0)
	v_mfma_f32_32x32x16_bf16 v[16:31], v[4:7], v[112:115], v[16:31]
	ds_read_b128 v[0:3], v203 offset:32768
	ds_read_b128 v[4:7], v203 offset:40960
	s_waitcnt lgkmcnt(1)
	v_mfma_f32_32x32x16_bf16 v[32:47], v[0:3], v[108:111], v[32:47]
	v_bitop3_b32 v0, v176, v62, s46 bitop3:0x36
	v_add_u32_e32 v204, v61, v0
	s_waitcnt lgkmcnt(0)
	v_mfma_f32_32x32x16_bf16 v[16:31], v[4:7], v[108:111], v[16:31]
	ds_read_b128 v[0:3], v204 offset:32768
	ds_read_b128 v[4:7], v204 offset:40960
	s_waitcnt lgkmcnt(1)
	v_mfma_f32_32x32x16_bf16 v[32:47], v[0:3], v[104:107], v[32:47]
	v_bitop3_b32 v0, v176, v62, s42 bitop3:0x36
	v_add_u32_e32 v205, v61, v0
	ds_read_b128 v[50:53], v205 offset:32768
	ds_read_b128 v[54:57], v205 offset:40960
	s_waitcnt lgkmcnt(1)
; #define SLOAD(i, k0) do { sr_[i].vs0 = *reinterpret_cast<const bf16x8*>(vptr + (size_t)((k0) + sr) * vstr); \
;     sr_[i].vs1 = *reinterpret_cast<const bf16x8*>(vptr + (size_t)((k0) + 32 + sr) * vstr); \
;     sr_[i].ks0 = *reinterpret_cast<const bf16x8*>(kptr + (size_t)((k0) + sr) * kstr); \
;     sr_[i].ks1 = *reinterpret_cast<const bf16x8*>(kptr + (size_t)((k0) + 32 + sr) * kstr); } while (0)
; #define SWRITE(b, i) do { *(LAS bf16x8*)(V_lds + (b) * SHM_V + vst0) = sr_[i].vs0;          \
;     *(LAS bf16x8*)(V_lds + (b) * SHM_V + vst1) = sr_[i].vs1; const int kc = sc * 2;               \
;     *(LAS bf16x8*)(K_lds + (b) * SHM_K + KSWZ(sr, kc)) = sr_[i].ks0;                       \
;     *(LAS bf16x8*)(K_lds + (b) * SHM_K + KSWZ(32 + sr, kc)) = sr_[i].ks1; } while (0)
; #define SWAIT() asm volatile("s_waitcnt vmcnt(4)" ::: "memory")
; __device__ __forceinline__ void partialSM(f32x16& p0, f32x16& p1, float& m_reg, float& mn, float& alpha, float C, float thr) {
;   float pmax = p0[0];
; #pragma unroll
;   for (int r = 1; r < 16; ++r) pmax = fmaxf(pmax, p0[r]);
; #pragma unroll
;   for (int r = 0; r < 16; ++r) pmax = fmaxf(pmax, p1[r]);
;   { auto rr = __builtin_amdgcn_permlane32_swap(__float_as_uint(pmax), __float_as_uint(pmax), false, false);
;     pmax = fmaxf(__uint_as_float(rr[0]), __uint_as_float(rr[1])); }
;   if (__builtin_expect(__all(pmax - m_reg <= thr), 1)) { mn = m_reg; alpha = 1.f; }
;   else { mn = fmaxf(m_reg, pmax); alpha = __builtin_amdgcn_exp2f((m_reg - mn) * C); m_reg = mn; }
;   const float mnC = -mn * C;
; #pragma unroll
;   for (int r = 0; r < 16; ++r) p0[r] = fmaf(p0[r], C, mnC);
; #pragma unroll
;   for (int r = 0; r < 16; ++r) p1[r] = fmaf(p1[r], C, mnC);
; #pragma unroll
;   for (int r = 0; r < 16; ++r) p0[r] = __builtin_amdgcn_exp2f(p0[r]);
; }
; template <int NDQ, int NDV> ...
;     ...
;   qkt<NDQ>(pA0, pA1, K_lds, qr, r32, hi); partialSM(pA0, pA1, m_reg, mnA, alA, Cs, thr);
;   SLOAD(SO, 64); if (2 < NT) SLOAD(SE, 128);
;   SWAIT(); SWRITE(1, SO); __syncthreads();
	v_mfma_f32_32x32x16_bf16 v[32:47], v[50:53], v[100:103], v[32:47]
	v_bitop3_b32 v50, v176, v62, s47 bitop3:0x36
	v_add_u32_e32 v206, v61, v50
	ds_read_b128 v[50:53], v206 offset:32768
	v_add_u32_e32 v61, 64, v70
	v_mfma_f32_32x32x16_bf16 v[16:31], v[4:7], v[104:107], v[16:31]
	v_mov_b64_e32 v[0:1], s[12:13]
	v_mov_b64_e32 v[14:15], s[26:27]
	v_mov_b64_e32 v[2:3], s[14:15]
	v_mov_b64_e32 v[4:5], s[16:17]
	v_mov_b64_e32 v[6:7], s[18:19]
	v_mov_b64_e32 v[8:9], s[20:21]
	v_mov_b64_e32 v[10:11], s[22:23]
	s_waitcnt lgkmcnt(1)
	v_mfma_f32_32x32x16_bf16 v[16:31], v[54:57], v[100:103], v[16:31]
	ds_read_b128 v[54:57], v206 offset:40960
	v_mov_b64_e32 v[12:13], s[24:25]
	s_waitcnt lgkmcnt(1)
	v_mfma_f32_32x32x16_bf16 v[32:47], v[50:53], v[96:99], v[32:47]
	v_and_or_b32 v50, v59, 24, v60
	v_and_b32_e32 v51, 0x100, v59
	v_or3_b32 v72, v50, v58, v51
	v_mad_i64_i32 v[58:59], s[0:1], v61, s40, v[48:49]
	global_load_dwordx4 v[50:53], v[58:59], off offset:2560
	v_add_u32_e32 v194, 0, v72
	s_waitcnt lgkmcnt(0)
	v_mfma_f32_32x32x16_bf16 v[16:31], v[54:57], v[96:99], v[16:31]
	s_nop 3
	v_max_f32_e32 v54, v33, v33
	v_max_f32_e32 v55, v32, v32
	v_max_f32_e32 v54, v55, v54
	v_max3_f32 v54, v54, v34, v35
	v_max3_f32 v54, v54, v36, v37
	v_max3_f32 v54, v54, v38, v39
	v_max3_f32 v54, v54, v40, v41
	v_max3_f32 v54, v54, v42, v43
	v_max3_f32 v54, v54, v44, v45
	v_max3_f32 v54, v54, v46, v47
	v_max3_f32 v68, v54, v16, v17
	v_max3_f32 v68, v68, v18, v19
	v_max3_f32 v68, v68, v20, v21
	v_max3_f32 v68, v68, v22, v23
	v_max3_f32 v68, v68, v24, v25
	v_max3_f32 v68, v68, v26, v27
	v_add_u32_e32 v54, 0x60, v70
	v_max3_f32 v73, v68, v28, v29
	v_add_u32_e32 v68, 0xa0, v70
	v_mad_i64_i32 v[62:63], s[0:1], v54, s40, v[48:49]
	v_mad_i64_i32 v[68:69], s[0:1], v68, s40, v[48:49]
	v_add_u32_e32 v70, 0x80, v70
	global_load_dwordx4 v[54:57], v[62:63], off offset:2560
	s_nop 0
	global_load_dwordx4 v[58:61], v[58:59], off offset:2048
	s_nop 0
	global_load_dwordx4 v[62:65], v[62:63], off offset:2048
	v_mad_i64_i32 v[48:49], s[0:1], v70, s40, v[48:49]
	global_load_dwordx4 v[132:135], v[68:69], off offset:2048
	global_load_dwordx4 v[136:139], v[68:69], off offset:2560
	global_load_dwordx4 v[140:143], v[48:49], off offset:2048
	global_load_dwordx4 v[128:131], v[48:49], off offset:2560
	v_max3_f32 v48, v73, v30, v31
	v_mov_b32_e32 v49, v48
	s_nop 1
	v_permlane32_swap_b32_e32 v48, v49
	v_max_f32_e32 v49, v49, v49
	v_max_f32_e32 v48, v48, v48
	v_max_f32_e32 v48, v48, v49
	v_add_f32_e32 v49, 0x7149f2ca, v48
	v_max_f32_e32 v48, 0xf149f2ca, v48
	v_cmp_ge_f32_e32 vcc, s48, v49
	v_sub_f32_e32 v49, 0xf149f2ca, v48
	v_mul_f32_e32 v49, 0x3e0293ee, v49
	v_exp_f32_e32 v49, v49
	s_cmp_eq_u64 vcc, exec
	s_cselect_b64 vcc, -1, 0
	v_cndmask_b32_e32 v160, v48, v186, vcc
	v_mul_f32_e32 v48, 0xbe0293ee, v160
	v_cndmask_b32_e64 v207, v49, 1.0, vcc
	v_mov_b32_e32 v49, v48
	v_fmamk_f32 v32, v32, 0x3e0293ee, v48
	v_fmamk_f32 v33, v33, 0x3e0293ee, v48
	v_fmamk_f32 v34, v34, 0x3e0293ee, v48
	v_fmamk_f32 v35, v35, 0x3e0293ee, v48
	v_fmamk_f32 v36, v36, 0x3e0293ee, v48
	v_fmamk_f32 v37, v37, 0x3e0293ee, v48
	v_fmamk_f32 v38, v38, 0x3e0293ee, v48
	v_fmamk_f32 v39, v39, 0x3e0293ee, v48
	v_fmamk_f32 v40, v40, 0x3e0293ee, v48
	v_fmamk_f32 v41, v41, 0x3e0293ee, v48
	v_fmamk_f32 v42, v42, 0x3e0293ee, v48
	v_fmamk_f32 v43, v43, 0x3e0293ee, v48
	v_fmamk_f32 v44, v44, 0x3e0293ee, v48
	v_fmamk_f32 v45, v45, 0x3e0293ee, v48
	v_fmamk_f32 v46, v46, 0x3e0293ee, v48
	v_fmac_f32_e32 v49, 0x3e0293ee, v47
	v_pk_fma_f32 v[154:155], v[16:17], s[4:5], v[48:49] op_sel_hi:[1,0,0]
	v_exp_f32_e32 v175, v32
	v_exp_f32_e32 v214, v33
	v_exp_f32_e32 v173, v34
	v_exp_f32_e32 v211, v35
	v_exp_f32_e32 v172, v36
	v_exp_f32_e32 v174, v37
	v_exp_f32_e32 v170, v38
	v_exp_f32_e32 v171, v39
	v_exp_f32_e32 v167, v40
	v_exp_f32_e32 v169, v41
	v_exp_f32_e32 v166, v42
	v_exp_f32_e32 v168, v43
	v_exp_f32_e32 v163, v44
	v_exp_f32_e32 v165, v45
	v_exp_f32_e32 v162, v46
	v_exp_f32_e32 v164, v49
	v_mad_i64_i32 v[16:17], s[30:31], s3, v187, v[66:67]
	s_waitcnt vmcnt(4)
	v_lshl_or_b32 v16, s2, 6, v16
	v_pk_fma_f32 v[150:151], v[30:31], s[4:5], v[48:49] op_sel_hi:[1,0,0]
	v_pk_fma_f32 v[156:157], v[28:29], s[4:5], v[48:49] op_sel_hi:[1,0,0]
	v_pk_fma_f32 v[158:159], v[26:27], s[4:5], v[48:49] op_sel_hi:[1,0,0]
	v_pk_fma_f32 v[144:145], v[24:25], s[4:5], v[48:49] op_sel_hi:[1,0,0]
	v_pk_fma_f32 v[146:147], v[22:23], s[4:5], v[48:49] op_sel_hi:[1,0,0]
	v_pk_fma_f32 v[148:149], v[20:21], s[4:5], v[48:49] op_sel_hi:[1,0,0]
	v_pk_fma_f32 v[152:153], v[18:19], s[4:5], v[48:49] op_sel_hi:[1,0,0]
	s_waitcnt vmcnt(7)
	ds_write_b128 v197, v[50:53] offset:16384
	s_waitcnt vmcnt(6)
	ds_write_b128 v198, v[54:57] offset:16384
	s_waitcnt vmcnt(5)
	ds_write_b128 v195, v[58:61] offset:49152
	s_waitcnt vmcnt(4)
	ds_write_b128 v196, v[62:65] offset:49152
	v_lshl_add_u64 v[184:185], v[178:179], 0, v[16:17]
	v_mov_b64_e32 v[62:63], v[14:15]
	v_mov_b64_e32 v[46:47], v[14:15]
	v_mov_b64_e32 v[30:31], v[14:15]
	v_cmp_gt_u32_e64 s[0:1], 32, v71
	v_add_u32_e32 v193, s75, v72
	v_mov_b64_e32 v[60:61], v[12:13]
	v_mov_b64_e32 v[58:59], v[10:11]
	v_mov_b64_e32 v[56:57], v[8:9]
	v_mov_b64_e32 v[54:55], v[6:7]
	v_mov_b64_e32 v[52:53], v[4:5]
	v_mov_b64_e32 v[50:51], v[2:3]
	v_mov_b64_e32 v[48:49], v[0:1]
	v_mov_b64_e32 v[44:45], v[12:13]
	v_mov_b64_e32 v[42:43], v[10:11]
	v_mov_b64_e32 v[40:41], v[8:9]
	v_mov_b64_e32 v[38:39], v[6:7]
	v_mov_b64_e32 v[36:37], v[4:5]
	v_mov_b64_e32 v[34:35], v[2:3]
	v_mov_b64_e32 v[32:33], v[0:1]
	v_mov_b64_e32 v[28:29], v[12:13]
	v_mov_b64_e32 v[26:27], v[10:11]
	v_mov_b64_e32 v[24:25], v[8:9]
	v_mov_b64_e32 v[22:23], v[6:7]
	v_mov_b64_e32 v[20:21], v[4:5]
	v_mov_b64_e32 v[18:19], v[2:3]
	v_mov_b64_e32 v[16:17], v[0:1]
	v_mov_b32_e32 v236, v175
	v_mov_b32_e32 v237, v214
	v_mov_b32_e32 v238, v173
	v_mov_b32_e32 v239, v211
	v_mov_b32_e32 v240, v172
	v_mov_b32_e32 v241, v174
	v_mov_b32_e32 v242, v170
	v_mov_b32_e32 v243, v171
	v_mov_b32_e32 v244, v167
	v_mov_b32_e32 v245, v169
	v_mov_b32_e32 v246, v166
	v_mov_b32_e32 v247, v168
	v_mov_b32_e32 v248, v163
	v_mov_b32_e32 v249, v165
	v_mov_b32_e32 v250, v162
	v_mov_b32_e32 v251, v164
	s_waitcnt lgkmcnt(0)
	s_barrier
